# expert phase: per-token H row (read once) loaded with nt
# baseline (speedup 1.0000x reference)
; __device__ __forceinline__ float bf_lo(unsigned w) { return __uint_as_float(w << 16); }
; __device__ __forceinline__ float bf_hi(unsigned w) { return __uint_as_float(w & 0xffff0000u); }
; __device__ __forceinline__ unsigned xb_ld(unsigned* p)              { return __hip_atomic_load(p, __ATOMIC_RELAXED, __HIP_MEMORY_SCOPE_AGENT); }
; __device__ __forceinline__ void peer_expert_tokens(const Ctx& F, CParams& P, int layer, int m_rows_all, bool last, bool dry, bool hide, unsigned* selflag, int k_lo, int k_hi) {
;     ...
;         float hf[32];
; #pragma unroll
;         for (int j = 0; j < 8; ++j) { hf[j * 4 + 0] = bf_lo(hp4[j].x); hf[j * 4 + 1] = bf_hi(hp4[j].x); hf[j * 4 + 2] = bf_lo(hp4[j].y); hf[j * 4 + 3] = bf_hi(hp4[j].y); }
;         const float cgk0 = gk0, cgk1 = gk1;
;         const float su0 = SU[id0], sv0 = SV[id0], su1 = SU[id1], sv1 = SV[id1];
;         int nid0, nid1; float ngk0, ngk1;
;         if (hide && tq >= TL) {
;             { unsigned sp = 0u; while (xb_ld(selflag) < (unsigned)((TT - TL) / 64 * 8)) { __builtin_amdgcn_s_sleep(1); if (++sp > XB_SPIN_CAP) break; } }
;             __builtin_amdgcn_fence(__ATOMIC_ACQUIRE, "agent");
;             nid0 = __hip_atomic_load(PIDX + (size_t)tq * 128 + lane, __ATOMIC_RELAXED, __HIP_MEMORY_SCOPE_AGENT); nid1 = __hip_atomic_load(PIDX + (size_t)tq * 128 + 64 + lane, __ATOMIC_RELAXED, __HIP_MEMORY_SCOPE_AGENT);
;             ngk0 = __int_as_float(__hip_atomic_load((const int*)PG + (size_t)tq * 128 + lane, __ATOMIC_RELAXED, __HIP_MEMORY_SCOPE_AGENT)); ngk1 = __int_as_float(__hip_atomic_load((const int*)PG + (size_t)tq * 128 + 64 + lane, __ATOMIC_RELAXED, __HIP_MEMORY_SCOPE_AGENT));
;         } else { nid0 = PIDX[(size_t)tq * 128 + lane]; nid1 = PIDX[(size_t)tq * 128 + 64 + lane]; ngk0 = PG[(size_t)tq * 128 + lane]; ngk1 = PG[(size_t)tq * 128 + 64 + lane]; }
;         { const bf16_t* hp = H + (size_t)tq * DM + (unsigned)lane * 4u;
; #pragma unroll
;           for (int j = 0; j < 8; ++j) hp4[j] = *(const u32x2*)(hp + j * 256); }
.LBB0_2890:
	s_lshl_b64 s[14:15], s[14:15], 12
	v_lshl_add_u64 v[0:1], v[88:89], 0, s[14:15]
	v_lshlrev_b32_e32 v144, 16, v104
	v_and_b32_e32 v145, 0xffff0000, v104
	v_lshlrev_b32_e32 v146, 16, v105
	v_and_b32_e32 v147, 0xffff0000, v105
	v_lshlrev_b32_e32 v148, 16, v102
	v_and_b32_e32 v149, 0xffff0000, v102
	v_lshlrev_b32_e32 v150, 16, v103
	v_and_b32_e32 v151, 0xffff0000, v103
	v_lshlrev_b32_e32 v152, 16, v100
	v_and_b32_e32 v153, 0xffff0000, v100
	v_lshlrev_b32_e32 v154, 16, v101
	v_and_b32_e32 v155, 0xffff0000, v101
	v_lshlrev_b32_e32 v156, 16, v98
	v_and_b32_e32 v157, 0xffff0000, v98
	v_lshlrev_b32_e32 v158, 16, v99
	v_and_b32_e32 v159, 0xffff0000, v99
	v_lshlrev_b32_e32 v160, 16, v96
	v_and_b32_e32 v161, 0xffff0000, v96
	v_lshlrev_b32_e32 v162, 16, v97
	v_and_b32_e32 v163, 0xffff0000, v97
	v_lshlrev_b32_e32 v164, 16, v94
	v_and_b32_e32 v165, 0xffff0000, v94
	v_lshlrev_b32_e32 v166, 16, v95
	v_and_b32_e32 v167, 0xffff0000, v95
	v_lshlrev_b32_e32 v168, 16, v92
	v_and_b32_e32 v169, 0xffff0000, v92
	v_lshlrev_b32_e32 v170, 16, v93
	v_and_b32_e32 v171, 0xffff0000, v93
	v_lshlrev_b32_e32 v172, 16, v90
	v_and_b32_e32 v173, 0xffff0000, v90
	v_lshlrev_b32_e32 v174, 16, v91
	v_and_b32_e32 v175, 0xffff0000, v91
	global_load_dwordx2 v[104:105], v[0:1], off nt
	global_load_dwordx2 v[102:103], v[0:1], off offset:512 nt
	global_load_dwordx2 v[100:101], v[0:1], off offset:1024 nt
	global_load_dwordx2 v[98:99], v[0:1], off offset:1536 nt
	global_load_dwordx2 v[96:97], v[0:1], off offset:2048 nt
	global_load_dwordx2 v[94:95], v[0:1], off offset:2560 nt
	global_load_dwordx2 v[92:93], v[0:1], off offset:3072 nt
	global_load_dwordx2 v[90:91], v[0:1], off offset:3584 nt
	v_mov_b32_e32 v0, 0
	s_mov_b32 s15, -8
	v_mov_b32_e32 v184, 0
